# MLA loop: V-tile LDS write addresses computed before the barrier and ds_writes issued first inside the barrier-bounded staging zone (exps overlap the write latency)
# speedup vs baseline: 1.0224x; 1.0049x over previous
; #define WAIT_V0() asm volatile("s_waitcnt vmcnt(0)" ::: "memory")
; #define SWRITE(b) do { FRESH_COORDS(); \
;     if constexpr (!KDMA) { _Pragma("unroll") for (int i = 0; i < KC; ++i) *reinterpret_cast<bf16x8*>(shm + (b) * SHM_K + klo[i]) = ks[i]; } \
;     _Pragma("unroll") for (int i = 0; i < VC; ++i) *reinterpret_cast<bf16x8*>(shm + (b) * SHM_V + vlo[i]) = vs[i]; } while (0)
; template <int NCB> __device__ __forceinline__ int v_st(int k, int c) {
;   const int kk = (k & ~0xC) | ((k & 4) << 1) | ((k & 8) >> 1);
;   return ((kk >> 3) * NCB + (c >> 5)) * 512 + ((kk & 7) * 32 + (c & 31)) * 2;
; }
;     ...
;     partialSM<GM>(pB0, pB1, NEEDMASK(kb), kb, L, qpos, hi);
;     __syncthreads(); WAIT_V0(); SWRITE(0);
;     __syncthreads();
.LBB0_371:
	v_mov_b32_e32 v96, v161
	v_ashrrev_i32_e32 v97, 4, v96
	v_and_b32_e32 v99, 0xfffff0, v97
	v_lshlrev_b32_e32 v100, 1, v97
	v_add_u32_e32 v98, 32, v97
	v_and_or_b32 v99, v100, 8, v99
	v_lshrrev_b32_e32 v100, 1, v97
	v_and_b32_e32 v97, 3, v97
	v_and_or_b32 v97, v100, 4, v97
	v_and_b32_e32 v100, 0xfffff0, v98
	v_lshlrev_b32_e32 v98, 1, v98
	v_and_or_b32 v98, v98, 8, v100
	v_lshrrev_b32_e32 v99, 1, v99
	v_bfe_u32 v101, v96, 2, 2
	v_lshrrev_b32_e32 v98, 1, v98
	v_or_b32_e32 v99, v99, v101
	v_lshlrev_b32_e32 v96, 4, v96
	v_or_b32_e32 v98, v98, v101
	v_lshlrev_b32_e32 v99, 9, v99
	v_lshlrev_b32_e32 v97, 6, v97
	v_and_b32_e32 v96, 48, v96
	v_lshlrev_b32_e32 v98, 9, v98
	v_or3_b32 v99, v99, v97, v96
	v_or3_b32 v96, v98, v97, v96
	s_waitcnt vmcnt(0)
	s_barrier
	s_waitcnt vmcnt(0)
	ds_write_b128 v99, v[112:115]
	ds_write_b128 v96, v[116:119]
	v_exp_f32_e32 v64, v64
	v_exp_f32_e32 v66, v66
	v_exp_f32_e32 v68, v68
	v_exp_f32_e32 v70, v70
	v_exp_f32_e32 v72, v72
	v_exp_f32_e32 v74, v74
	v_exp_f32_e32 v76, v76
	v_exp_f32_e32 v78, v78
	v_exp_f32_e32 v65, v65
	v_exp_f32_e32 v67, v67
	v_exp_f32_e32 v69, v69
	v_exp_f32_e32 v71, v71
	v_exp_f32_e32 v73, v73
	v_exp_f32_e32 v75, v75
	v_exp_f32_e32 v77, v77
	v_exp_f32_e32 v79, v79
	s_waitcnt lgkmcnt(0)
	s_barrier
; #define SBAR() __builtin_amdgcn_sched_barrier(0)
; #define QKT(P0, P1, BUF) qkt<DQK, QL>(P0, P1, shm + K_OFF + (BUF) * SHM_K, qr, qlds, kofs, negM)
;     ...
;     if constexpr (ONEP) { finishSM(pB0, pB1, l_reg, pa0, pa1, pa2, pa3); SBAR(); QKT(pA0, pA1, 0); }
;     else { QKT(pA0, pA1, 0); finishSM(pB0, pB1, l_reg, pa0, pa1, pa2, pa3); }
;     SBAR();
;     if (j + 2 < NT) SLOAD(TKEY(j + 2), 1);
	v_add_f32_e32 v96, 0, v64
	v_add_f32_e32 v96, v65, v96
	v_add_f32_e32 v96, v66, v96
	v_add_f32_e32 v96, v67, v96
	v_add_f32_e32 v96, v68, v96
	v_add_f32_e32 v96, v69, v96
	v_add_f32_e32 v96, v70, v96
	v_add_f32_e32 v96, v71, v96
	v_add_f32_e32 v96, v72, v96
	v_add_f32_e32 v96, v73, v96
	v_add_f32_e32 v96, v74, v96
	v_add_f32_e32 v96, v75, v96
	v_exp_f32_e32 v80, v80
	v_add_f32_e32 v96, v76, v96
	v_exp_f32_e32 v81, v81
	v_add_f32_e32 v96, v77, v96
	v_exp_f32_e32 v82, v82
	v_add_f32_e32 v96, v78, v96
	v_exp_f32_e32 v83, v83
	v_add_f32_e32 v96, v79, v96
	v_exp_f32_e32 v84, v84
	v_add_f32_e32 v96, v80, v96
	v_exp_f32_e32 v85, v85
	v_add_f32_e32 v96, v81, v96
	v_exp_f32_e32 v86, v86
	v_add_f32_e32 v96, v82, v96
	v_exp_f32_e32 v87, v87
	v_add_f32_e32 v96, v83, v96
	v_exp_f32_e32 v88, v88
	v_add_f32_e32 v96, v84, v96
	v_exp_f32_e32 v89, v89
	v_add_f32_e32 v96, v85, v96
	v_exp_f32_e32 v90, v90
	v_add_f32_e32 v96, v86, v96
	v_exp_f32_e32 v91, v91
	v_add_f32_e32 v96, v87, v96
	v_exp_f32_e32 v92, v92
	v_add_f32_e32 v96, v88, v96
	v_exp_f32_e32 v93, v93
	v_add_f32_e32 v96, v89, v96
	v_exp_f32_e32 v94, v94
	v_add_f32_e32 v96, v90, v96
	v_exp_f32_e32 v95, v95
	v_add_f32_e32 v96, v91, v96
	v_add_f32_e32 v96, v92, v96
	v_add_f32_e32 v96, v93, v96
	v_add_f32_e32 v96, v94, v96
	v_add_f32_e32 v179, v95, v96
	v_mov_b32_e32 v180, v179
	v_cvt_pk_bf16_f32 v120, v64, v65
	v_cvt_pk_bf16_f32 v121, v66, v67
	v_cvt_pk_bf16_f32 v122, v68, v69
	v_cvt_pk_bf16_f32 v123, v70, v71
	v_cvt_pk_bf16_f32 v124, v72, v73
	v_cvt_pk_bf16_f32 v125, v74, v75
	v_cvt_pk_bf16_f32 v126, v76, v77
	v_cvt_pk_bf16_f32 v127, v78, v79
	v_cvt_pk_bf16_f32 v142, v80, v81
	v_cvt_pk_bf16_f32 v143, v82, v83
	v_cvt_pk_bf16_f32 v144, v84, v85
	v_cvt_pk_bf16_f32 v145, v86, v87
	v_cvt_pk_bf16_f32 v146, v88, v89
	v_cvt_pk_bf16_f32 v147, v90, v91
	v_cvt_pk_bf16_f32 v148, v92, v93
	v_cvt_pk_bf16_f32 v149, v94, v95
	s_nop 1
	v_permlane32_swap_b32_e32 v179, v180
	v_permlane32_swap_b32_e32 v120, v122
	v_permlane32_swap_b32_e32 v121, v123
	v_permlane32_swap_b32_e32 v124, v126
	v_permlane32_swap_b32_e32 v125, v127
	v_permlane32_swap_b32_e32 v142, v144
	v_permlane32_swap_b32_e32 v143, v145
	v_permlane32_swap_b32_e32 v146, v148
	v_permlane32_swap_b32_e32 v147, v149
	ds_read_b128 v[64:67], v152 offset:32768
	ds_read_b128 v[172:175], v152 offset:45056
	v_mov_b64_e32 v[110:111], s[18:19]
	v_mov_b64_e32 v[108:109], s[16:17]
	v_mov_b64_e32 v[106:107], s[14:15]
	v_mov_b64_e32 v[104:105], s[12:13]
	v_mov_b64_e32 v[102:103], s[10:11]
	v_mov_b64_e32 v[100:101], s[8:9]
	v_mov_b64_e32 v[98:99], s[6:7]
	v_mov_b64_e32 v[96:97], s[4:5]
	s_waitcnt lgkmcnt(1)
	s_nop 0
	v_mfma_f32_32x32x16_bf16 v[80:95], v[64:67], v[138:141], v[96:111]
	s_waitcnt lgkmcnt(0)
	v_mfma_f32_32x32x16_bf16 v[64:79], v[172:175], v[138:141], v[96:111]
	s_nop 6
	ds_read_b128 v[96:99], v156 offset:32768
	ds_read_b128 v[100:103], v156 offset:45056
	s_waitcnt lgkmcnt(1)
	v_mfma_f32_32x32x16_bf16 v[80:95], v[96:99], v[134:137], v[80:95]
	s_waitcnt lgkmcnt(0)
	v_mfma_f32_32x32x16_bf16 v[64:79], v[100:103], v[134:137], v[64:79]
	ds_read_b128 v[96:99], v155 offset:32768
	ds_read_b128 v[100:103], v155 offset:45056
	s_waitcnt lgkmcnt(1)
	v_mfma_f32_32x32x16_bf16 v[80:95], v[96:99], v[130:133], v[80:95]
	s_waitcnt lgkmcnt(0)
	v_mfma_f32_32x32x16_bf16 v[64:79], v[100:103], v[130:133], v[64:79]
	ds_read_b128 v[96:99], v153 offset:32768
	ds_read_b128 v[100:103], v153 offset:45056
	ds_read_b128 v[104:107], v167
	s_waitcnt lgkmcnt(0)
	v_mfma_f32_32x32x16_bf16 v[80:95], v[96:99], v[104:107], v[80:95]
	v_mfma_f32_32x32x16_bf16 v[64:79], v[100:103], v[104:107], v[64:79]
	ds_read_b128 v[96:99], v152 offset:32896
	ds_read_b128 v[100:103], v152 offset:45184
	ds_read_b128 v[104:107], v167 offset:1024
	s_waitcnt lgkmcnt(0)
	v_mfma_f32_32x32x16_bf16 v[80:95], v[96:99], v[104:107], v[80:95]
	v_mfma_f32_32x32x16_bf16 v[64:79], v[100:103], v[104:107], v[64:79]
	ds_read_b128 v[96:99], v156 offset:32896
	ds_read_b128 v[100:103], v156 offset:45184
	ds_read_b128 v[104:107], v167 offset:2048
	s_waitcnt lgkmcnt(0)
	v_mfma_f32_32x32x16_bf16 v[80:95], v[96:99], v[104:107], v[80:95]
	v_mfma_f32_32x32x16_bf16 v[64:79], v[100:103], v[104:107], v[64:79]
	ds_read_b128 v[96:99], v155 offset:32896
	ds_read_b128 v[100:103], v155 offset:45184
	ds_read_b128 v[104:107], v167 offset:3072
	s_waitcnt lgkmcnt(0)
	v_mfma_f32_32x32x16_bf16 v[80:95], v[96:99], v[104:107], v[80:95]
	v_mfma_f32_32x32x16_bf16 v[64:79], v[100:103], v[104:107], v[64:79]
	ds_read_b128 v[96:99], v153 offset:32896
	ds_read_b128 v[100:103], v153 offset:45184
	ds_read_b128 v[104:107], v167 offset:4096
	s_waitcnt lgkmcnt(0)
	v_mfma_f32_32x32x16_bf16 v[80:95], v[96:99], v[104:107], v[80:95]
	v_mfma_f32_32x32x16_bf16 v[64:79], v[100:103], v[104:107], v[64:79]
	ds_read_b128 v[96:99], v152 offset:33024
	ds_read_b128 v[100:103], v152 offset:45312
	ds_read_b128 v[104:107], v167 offset:5120
	s_waitcnt lgkmcnt(0)
	v_mfma_f32_32x32x16_bf16 v[80:95], v[96:99], v[104:107], v[80:95]
	v_mfma_f32_32x32x16_bf16 v[64:79], v[100:103], v[104:107], v[64:79]
	ds_read_b128 v[96:99], v156 offset:33024
	ds_read_b128 v[100:103], v156 offset:45312
	ds_read_b128 v[104:107], v167 offset:6144
	s_waitcnt lgkmcnt(0)
	v_mfma_f32_32x32x16_bf16 v[80:95], v[96:99], v[104:107], v[80:95]
	v_mfma_f32_32x32x16_bf16 v[64:79], v[100:103], v[104:107], v[64:79]
	ds_read_b128 v[96:99], v155 offset:33024
	ds_read_b128 v[100:103], v155 offset:45312
	ds_read_b128 v[104:107], v167 offset:7168
	s_waitcnt lgkmcnt(0)
	v_mfma_f32_32x32x16_bf16 v[80:95], v[96:99], v[104:107], v[80:95]
	v_mfma_f32_32x32x16_bf16 v[64:79], v[100:103], v[104:107], v[64:79]
	ds_read_b128 v[96:99], v153 offset:33024
	ds_read_b128 v[100:103], v153 offset:45312
	ds_read_b128 v[104:107], v167 offset:8192
	s_waitcnt lgkmcnt(0)
	v_mfma_f32_32x32x16_bf16 v[80:95], v[96:99], v[104:107], v[80:95]
	v_mfma_f32_32x32x16_bf16 v[64:79], v[100:103], v[104:107], v[64:79]
	s_cmp_lt_u32 s3, s58
	s_cselect_b64 s[22:23], -1, 0
	s_cmp_ge_u32 s3, s58
	s_cselect_b64 s[20:21], -1, 0
	s_and_b64 vcc, exec, s[20:21]
	s_cbranch_vccnz .LBB0_373
	s_add_u32 s100, s72, s48
	s_addc_u32 s101, s73, s49
	v_readfirstlane_b32 s38, v168
	s_mov_b32 m0, s38
	s_nop 0
	global_load_lds_dwordx4 v235, s[100:101]
	s_add_i32 m0, s38, 0x2000
	s_nop 0
	global_load_lds_dwordx4 v236, s[100:101]
	s_add_i32 m0, s38, 0x4000
	s_nop 0
	global_load_lds_dwordx4 v237, s[100:101]
	s_add_u32 s100, s74, 0xd2bc000
	s_addc_u32 s101, s75, 0
	global_load_dwordx4 v[112:115], v232, s[100:101] offset:256
	s_add_u32 s100, s100, 0x8000
	s_addc_u32 s101, s101, 0
	global_load_dwordx4 v[116:119], v232, s[100:101] offset:256

; #define WAIT_V0() asm volatile("s_waitcnt vmcnt(0)" ::: "memory")
; #define SWRITE(b) do { FRESH_COORDS(); \
;     if constexpr (!KDMA) { _Pragma("unroll") for (int i = 0; i < KC; ++i) *reinterpret_cast<bf16x8*>(shm + (b) * SHM_K + klo[i]) = ks[i]; } \
;     _Pragma("unroll") for (int i = 0; i < VC; ++i) *reinterpret_cast<bf16x8*>(shm + (b) * SHM_V + vlo[i]) = vs[i]; } while (0)
;     ...
;     __syncthreads();
;     if (j + 2 < NT) { WAIT_V0(); SWRITE(1); }
;     __syncthreads();
.LBB0_375:
	v_mov_b32_e32 v96, v161
	v_ashrrev_i32_e32 v97, 4, v96
	v_and_b32_e32 v99, 0xfffff0, v97
	v_lshlrev_b32_e32 v100, 1, v97
	v_add_u32_e32 v98, 32, v97
	v_and_or_b32 v99, v100, 8, v99
	v_lshrrev_b32_e32 v100, 1, v97
	v_and_b32_e32 v97, 3, v97
	v_and_or_b32 v97, v100, 4, v97
	v_and_b32_e32 v100, 0xfffff0, v98
	v_lshlrev_b32_e32 v98, 1, v98
	v_and_or_b32 v98, v98, 8, v100
	v_lshrrev_b32_e32 v99, 1, v99
	v_bfe_u32 v101, v96, 2, 2
	v_lshrrev_b32_e32 v98, 1, v98
	v_or_b32_e32 v99, v99, v101
	v_lshlrev_b32_e32 v96, 4, v96
	v_or_b32_e32 v98, v98, v101
	v_lshlrev_b32_e32 v99, 9, v99
	v_lshlrev_b32_e32 v97, 6, v97
	v_and_b32_e32 v96, 48, v96
	v_lshlrev_b32_e32 v98, 9, v98
	v_or3_b32 v99, v99, v97, v96
	v_or3_b32 v96, v98, v97, v96
	s_andn2_b64 vcc, exec, s[22:23]
	s_waitcnt vmcnt(0) lgkmcnt(0)
	s_barrier
	s_cbranch_vccnz .LBB0_377
	s_waitcnt vmcnt(0)
	ds_write_b128 v99, v[112:115] offset:16384
	ds_write_b128 v96, v[116:119] offset:16384
